# P4 attention: V^T fragment LDS reads issued at the loop header (behind the last K read) into their own registers
# speedup vs baseline: 1.0179x; 1.0044x over previous
; DI unsigned pack2bf(float a, float b) { const f2_t v = {a, b}; return __builtin_bit_cast(unsigned, __builtin_convertvector(v, bf2_t)); }
; DI void attn_task(const Params& P, int bh, int n, int t, int lane, const char* Ks, const char* Vs) {
;     ...
;   for (int kt = 0; kt < nkt; ++kt) {
;     const int kbase = n * 256 + kt * 32;
;     const int krow = kt * 32 + r;
;     f32x16 S;
; #pragma unroll
;     for (int i = 0; i < 16; ++i) S[i] = 0.f;
; #pragma unroll
;     for (int s = 0; s < 4; ++s) {
;       const bf16x8 kf = *reinterpret_cast<const bf16x8*>(Ks + krow * 128 + (((2 * s + hh) ^ ((krow >> 1) & 7)) * 16));
;       S = __builtin_amdgcn_mfma_f32_32x32x16_bf16(kf, qf[s], S, 0, 0, 0);
;     }
;     const bool diag = own && (kt == t);
;     constexpr float SC2 = 0.125f * 1.4426950408889634f;
;     float mx = -1e30f;
; #pragma unroll
;     for (int i = 0; i < 16; ++i) {
;       if (diag && (kbase + crow(i, hh) > lq)) S[i] = -1e30f;
;       mx = fmaxf(mx, S[i]);
;     }
;     mx = xor32_max(mx);
;     const float m_new = fmaxf(m_run, mx * SC2);
;     const float alpha = __builtin_amdgcn_exp2f(m_run - m_new);
;     float rs = 0.f;
; #pragma unroll
;     for (int i = 0; i < 16; ++i) { float pv = __builtin_amdgcn_exp2f(fmaf(S[i], SC2, -m_new)); S[i] = pv; rs += pv; }
;     rs = xor32_sum(rs);
;     l_run = l_run * alpha + rs; m_run = m_new;
;     if (__ballot(alpha != 1.f)) {
; #pragma unroll
;       for (int i = 0; i < 16; ++i) { O0[i] *= alpha; O1[i] *= alpha; }
;     }
; #pragma unroll
;     for (int s = 0; s < 2; ++s) {
;       const uint4 ppk = make_uint4(pack2bf(S[8 * s], S[8 * s + 1]), pack2bf(S[8 * s + 2], S[8 * s + 3]), pack2bf(S[8 * s + 4], S[8 * s + 5]), pack2bf(S[8 * s + 6], S[8 * s + 7]));
;       const bf16x8 pf = __builtin_bit_cast(bf16x8, ppk);
; #pragma unroll
;       for (int dt = 0; dt < 2; ++dt) {
;         const char* vp = Vs + (dt * 32 + r) * 528 + (kt * 32 + 16 * s + 4 * hh) * 2;
;         const uint2 lo = *reinterpret_cast<const uint2*>(vp), hi = *reinterpret_cast<const uint2*>(vp + 16);
;         const uint4 vv = make_uint4(lo.x, lo.y, hi.x, hi.y);
;         if (dt == 0) O0 = __builtin_amdgcn_mfma_f32_32x32x16_bf16(__builtin_bit_cast(bf16x8, vv), pf, O0, 0, 0, 0);
;         else O1 = __builtin_amdgcn_mfma_f32_32x32x16_bf16(__builtin_bit_cast(bf16x8, vv), pf, O1, 0, 0, 0);
;       }
;     }
.LBB0_782:
	v_cvt_pk_bf16_f32 v56, v4, v6
	v_cvt_pk_bf16_f32 v57, v8, v9
	v_cvt_pk_bf16_f32 v58, v12, v14
	v_cvt_pk_bf16_f32 v59, v48, v49
	v_add_f32_e32 v4, v50, v51
	v_cvt_pk_bf16_f32 v7, v5, v7
	s_waitcnt lgkmcnt(0)
	v_mfma_f32_32x32x16_bf16 v[16:31], v[216:219], v[56:59], v[16:31]
	v_cvt_pk_bf16_f32 v8, v10, v11
	v_cvt_pk_bf16_f32 v9, v13, v15
	s_add_i32 s8, s8, 32
	v_fmac_f32_e32 v4, v155, v0
	v_cmp_eq_u32_e32 vcc, s8, v146
	v_add_u32_e32 v154, 64, v154
	v_add_u32_e32 v153, 64, v153
	v_mfma_f32_32x32x16_bf16 v[32:47], v[220:223], v[56:59], v[32:47]
	v_cvt_pk_bf16_f32 v6, v2, v3
	v_add_u32_e32 v152, 0x1000, v152
	v_add_u32_e32 v151, 0x1000, v151
	v_add_u32_e32 v150, 0x1000, v150
	v_add_u32_e32 v149, 0x1000, v149
	s_or_b64 s[50:51], vcc, s[50:51]
	v_mfma_f32_32x32x16_bf16 v[16:31], v[224:227], v[6:9], v[16:31]
	v_mov_b32_e32 v155, v4
	v_mfma_f32_32x32x16_bf16 v[32:47], v[228:231], v[6:9], v[32:47]
	s_andn2_b64 exec, exec, s[50:51]
	s_cbranch_execz .LBB0_794
.LBB0_783:
	v_add_u32_e32 v0, v152, v197
	ds_read_b128 v[2:5], v0
	v_add_u32_e32 v0, v151, v197
	ds_read_b128 v[6:9], v0
	v_add_u32_e32 v10, v149, v197
	v_add_u32_e32 v11, s8, v145
	v_subrev_co_u32_e32 v144, vcc, 1, v144
	v_cmp_gt_i32_e64 s[0:1], v11, v148
	v_cmp_ge_i32_e64 s[6:7], v11, v148
	s_waitcnt vmcnt(3) lgkmcnt(1)
	v_mfma_f32_32x32x16_bf16 v[48:63], v[2:5], v[64:67], 0
	v_add_u32_e32 v2, v150, v197
	ds_read_b128 v[2:5], v2
	s_and_b64 s[0:1], vcc, s[0:1]
	v_add_u32_e32 v12, 3, v11
	v_add_u32_e32 v13, 8, v11
	v_cmp_gt_i32_e64 s[12:13], v12, v148
	v_add_u32_e32 v14, 9, v11
	s_waitcnt vmcnt(2) lgkmcnt(1)
	v_mfma_f32_32x32x16_bf16 v[48:63], v[6:9], v[68:71], v[48:63]
	ds_read_b128 v[6:9], v10
	v_add_u32_e32 v210, v153, v197
	v_add_u32_e32 v211, v154, v197
	ds_read2_b64 v[216:219], v210 offset1:2
	ds_read2_b64 v[220:223], v211 offset1:2
	ds_read2_b64 v[224:227], v210 offset0:4 offset1:6
	ds_read2_b64 v[228:231], v211 offset0:4 offset1:6
	v_add_u32_e32 v10, 2, v11
	v_cmp_gt_i32_e64 s[10:11], v10, v148
	v_cmp_gt_i32_e64 s[14:15], v13, v148
	v_cmp_gt_i32_e64 s[16:17], v14, v148
	v_mov_b32_e32 v0, v147
	s_waitcnt vmcnt(1) lgkmcnt(5)
	v_mfma_f32_32x32x16_bf16 v[48:63], v[2:5], v[72:75], v[48:63]
	v_add_u32_e32 v2, 10, v11
	v_cmp_gt_i32_e64 s[18:19], v2, v148
	v_add_u32_e32 v3, 11, v11
	s_waitcnt vmcnt(0) lgkmcnt(4)
	v_mfma_f32_32x32x16_bf16 v[48:63], v[6:9], v[76:79], v[48:63]
	v_add_u32_e32 v6, 16, v11
	s_nop 10
	v_cndmask_b32_e64 v2, v48, v143, s[0:1]
	s_and_b64 s[0:1], vcc, s[6:7]
	v_cndmask_b32_e64 v5, v49, v143, s[0:1]
	s_and_b64 s[0:1], vcc, s[10:11]
	v_cndmask_b32_e64 v7, v50, v143, s[0:1]
	s_and_b64 s[0:1], vcc, s[12:13]
	v_cndmask_b32_e64 v9, v51, v143, s[0:1]
	s_and_b64 s[0:1], vcc, s[14:15]
	v_cndmask_b32_e64 v10, v52, v143, s[0:1]
	s_and_b64 s[0:1], vcc, s[16:17]
	v_cndmask_b32_e64 v13, v53, v143, s[0:1]
	s_and_b64 s[0:1], vcc, s[18:19]
	v_cndmask_b32_e64 v15, v54, v143, s[0:1]
	v_cmp_gt_i32_e64 s[0:1], v3, v148
	s_and_b64 s[0:1], vcc, s[0:1]
	v_max3_f32 v4, v2, s22, v5
	v_cndmask_b32_e64 v3, v55, v143, s[0:1]
	v_cmp_gt_i32_e64 s[0:1], v6, v148
	s_and_b64 s[0:1], vcc, s[0:1]
	v_add_u32_e32 v6, 17, v11
	v_cndmask_b32_e64 v50, v56, v143, s[0:1]
	v_cmp_gt_i32_e64 s[0:1], v6, v148
	s_and_b64 s[0:1], vcc, s[0:1]
	v_add_u32_e32 v6, 18, v11
	v_cndmask_b32_e64 v51, v57, v143, s[0:1]
	v_cmp_gt_i32_e64 s[0:1], v6, v148
	s_and_b64 s[0:1], vcc, s[0:1]
	v_add_u32_e32 v6, 19, v11
	v_cndmask_b32_e64 v52, v58, v143, s[0:1]
	v_cmp_gt_i32_e64 s[0:1], v6, v148
	s_and_b64 s[0:1], vcc, s[0:1]
	v_add_u32_e32 v6, 24, v11
	v_cndmask_b32_e64 v53, v59, v143, s[0:1]
	v_cmp_gt_i32_e64 s[0:1], v6, v148
	s_and_b64 s[0:1], vcc, s[0:1]
	v_add_u32_e32 v6, 25, v11
	v_cndmask_b32_e64 v54, v60, v143, s[0:1]
	v_cmp_gt_i32_e64 s[0:1], v6, v148
	v_max3_f32 v4, v4, v7, v9
	s_and_b64 s[0:1], vcc, s[0:1]
	v_add_u32_e32 v6, 26, v11
	v_max3_f32 v4, v4, v10, v13
	v_cndmask_b32_e64 v55, v61, v143, s[0:1]
	v_cmp_gt_i32_e64 s[0:1], v6, v148
	v_max3_f32 v4, v4, v15, v3
	s_and_b64 s[0:1], vcc, s[0:1]
	v_add_u32_e32 v6, 27, v11
	v_max3_f32 v4, v4, v50, v51
	v_cndmask_b32_e64 v56, v62, v143, s[0:1]
	v_cmp_gt_i32_e64 s[0:1], v6, v148
	v_max3_f32 v4, v4, v52, v53
	s_and_b64 vcc, vcc, s[0:1]
	v_max3_f32 v4, v4, v54, v55
	v_cndmask_b32_e32 v57, v63, v143, vcc
	v_max3_f32 v4, v4, v56, v57
	v_mov_b32_e32 v6, v4
	s_nop 1
	v_permlane32_swap_b32_e32 v4, v6
	v_max_f32_e32 v6, v6, v6
	v_max_f32_e32 v4, v4, v4
	v_max_f32_e32 v4, v4, v6
	v_mul_f32_e32 v4, 0x3e38aa3b, v4
	v_max_f32_e32 v6, v0, v0
	v_max_f32_e32 v147, v6, v4
	v_fma_f32 v2, v2, s23, -v147
	v_exp_f32_e32 v4, v2
	v_fma_f32 v2, v5, s23, -v147
	v_exp_f32_e32 v6, v2
	v_fma_f32 v2, v7, s23, -v147
	v_exp_f32_e32 v8, v2
	v_fma_f32 v2, v9, s23, -v147
	v_exp_f32_e32 v9, v2
	v_fma_f32 v5, v10, s23, -v147
	v_add_f32_e32 v2, 0, v4
	v_exp_f32_e32 v12, v5
	v_fma_f32 v5, v13, s23, -v147
	v_add_f32_e32 v2, v6, v2
	v_exp_f32_e32 v14, v5
	v_fma_f32 v5, v15, s23, -v147
	v_add_f32_e32 v2, v8, v2
	v_exp_f32_e32 v48, v5
	v_fma_f32 v3, v3, s23, -v147
	v_add_f32_e32 v2, v9, v2
	v_exp_f32_e32 v49, v3
	v_add_f32_e32 v2, v12, v2
	v_add_f32_e32 v2, v14, v2
	v_add_f32_e32 v2, v48, v2
	v_add_f32_e32 v10, v49, v2
	v_fma_f32 v2, v50, s23, -v147
	v_exp_f32_e32 v2, v2
	v_fma_f32 v3, v51, s23, -v147
	v_exp_f32_e32 v3, v3
	v_fma_f32 v5, v52, s23, -v147
	v_exp_f32_e32 v5, v5
	v_fma_f32 v7, v53, s23, -v147
	v_exp_f32_e32 v7, v7
	v_add_f32_e32 v10, v2, v10
	v_add_f32_e32 v10, v3, v10
	v_add_f32_e32 v10, v5, v10
	v_add_f32_e32 v50, v7, v10
	v_fma_f32 v10, v54, s23, -v147
	v_exp_f32_e32 v10, v10
	v_fma_f32 v11, v55, s23, -v147
	v_exp_f32_e32 v11, v11
	v_fma_f32 v13, v56, s23, -v147
	v_exp_f32_e32 v13, v13
	v_fma_f32 v15, v57, s23, -v147
	v_exp_f32_e32 v15, v15
	v_sub_f32_e32 v0, v0, v147
	v_add_f32_e32 v50, v10, v50
	v_add_f32_e32 v50, v11, v50
	v_exp_f32_e32 v0, v0
	v_add_f32_e32 v50, v13, v50
	v_add_f32_e32 v50, v15, v50
	v_mov_b32_e32 v51, v50
	s_nop 1
	v_permlane32_swap_b32_e32 v50, v51
	v_cmp_neq_f32_e32 vcc, 1.0, v0
	s_cbranch_vccz .LBB0_782
	v_pk_mul_f32 v[30:31], v[30:31], v[0:1] op_sel_hi:[1,0]
	v_pk_mul_f32 v[28:29], v[28:29], v[0:1] op_sel_hi:[1,0]
	v_pk_mul_f32 v[26:27], v[26:27], v[0:1] op_sel_hi:[1,0]
	v_pk_mul_f32 v[24:25], v[24:25], v[0:1] op_sel_hi:[1,0]
	v_pk_mul_f32 v[22:23], v[22:23], v[0:1] op_sel_hi:[1,0]
	v_pk_mul_f32 v[20:21], v[20:21], v[0:1] op_sel_hi:[1,0]
	v_pk_mul_f32 v[18:19], v[18:19], v[0:1] op_sel_hi:[1,0]
	v_pk_mul_f32 v[16:17], v[16:17], v[0:1] op_sel_hi:[1,0]
	v_pk_mul_f32 v[46:47], v[46:47], v[0:1] op_sel_hi:[1,0]
	v_pk_mul_f32 v[44:45], v[44:45], v[0:1] op_sel_hi:[1,0]
	v_pk_mul_f32 v[42:43], v[42:43], v[0:1] op_sel_hi:[1,0]
	v_pk_mul_f32 v[40:41], v[40:41], v[0:1] op_sel_hi:[1,0]
	v_pk_mul_f32 v[38:39], v[38:39], v[0:1] op_sel_hi:[1,0]
	v_pk_mul_f32 v[36:37], v[36:37], v[0:1] op_sel_hi:[1,0]
	v_pk_mul_f32 v[34:35], v[34:35], v[0:1] op_sel_hi:[1,0]
	v_pk_mul_f32 v[32:33], v[32:33], v[0:1] op_sel_hi:[1,0]
	s_branch .LBB0_782

; DI unsigned pack2bf(float a, float b) { const f2_t v = {a, b}; return __builtin_bit_cast(unsigned, __builtin_convertvector(v, bf2_t)); }
; DI void attn_task(const Params& P, int bh, int n, int t, int lane, const char* Ks, const char* Vs) {
;     ...
;   for (int kt = 0; kt < nkt; ++kt) {
;     const int kbase = n * 256 + kt * 32;
;     const int krow = kt * 32 + r;
;     f32x16 S;
; #pragma unroll
;     for (int i = 0; i < 16; ++i) S[i] = 0.f;
; #pragma unroll
;     for (int s = 0; s < 4; ++s) {
;       const bf16x8 kf = *reinterpret_cast<const bf16x8*>(Ks + krow * 128 + (((2 * s + hh) ^ ((krow >> 1) & 7)) * 16));
;       S = __builtin_amdgcn_mfma_f32_32x32x16_bf16(kf, qf[s], S, 0, 0, 0);
;     }
;     const bool diag = own && (kt == t);
;     constexpr float SC2 = 0.125f * 1.4426950408889634f;
;     float mx = -1e30f;
; #pragma unroll
;     for (int i = 0; i < 16; ++i) {
;       if (diag && (kbase + crow(i, hh) > lq)) S[i] = -1e30f;
;       mx = fmaxf(mx, S[i]);
;     }
;     mx = xor32_max(mx);
;     const float m_new = fmaxf(m_run, mx * SC2);
;     const float alpha = __builtin_amdgcn_exp2f(m_run - m_new);
;     float rs = 0.f;
; #pragma unroll
;     for (int i = 0; i < 16; ++i) { float pv = __builtin_amdgcn_exp2f(fmaf(S[i], SC2, -m_new)); S[i] = pv; rs += pv; }
;     rs = xor32_sum(rs);
;     l_run = l_run * alpha + rs; m_run = m_new;
;     if (__ballot(alpha != 1.f)) {
; #pragma unroll
;       for (int i = 0; i < 16; ++i) { O0[i] *= alpha; O1[i] *= alpha; }
;     }
; #pragma unroll
;     for (int s = 0; s < 2; ++s) {
;       const uint4 ppk = make_uint4(pack2bf(S[8 * s], S[8 * s + 1]), pack2bf(S[8 * s + 2], S[8 * s + 3]), pack2bf(S[8 * s + 4], S[8 * s + 5]), pack2bf(S[8 * s + 6], S[8 * s + 7]));
;       const bf16x8 pf = __builtin_bit_cast(bf16x8, ppk);
; #pragma unroll
;       for (int dt = 0; dt < 2; ++dt) {
;         const char* vp = Vs + (dt * 32 + r) * 528 + (kt * 32 + 16 * s + 4 * hh) * 2;
;         const uint2 lo = *reinterpret_cast<const uint2*>(vp), hi = *reinterpret_cast<const uint2*>(vp + 16);
;         const uint4 vv = make_uint4(lo.x, lo.y, hi.x, hi.y);
;         if (dt == 0) O0 = __builtin_amdgcn_mfma_f32_32x32x16_bf16(__builtin_bit_cast(bf16x8, vv), pf, O0, 0, 0, 0);
;         else O1 = __builtin_amdgcn_mfma_f32_32x32x16_bf16(__builtin_bit_cast(bf16x8, vv), pf, O1, 0, 0, 0);
;       }
;     }
.LBB0_790:
	v_add_u32_e32 v0, v148, v197
	ds_read_b128 v[34:37], v0
	v_add_u32_e32 v0, v147, v197
	ds_read_b128 v[152:155], v0
	v_mov_b32_e32 v0, v71
	v_add_u32_e32 v71, v91, v197
	ds_read_b128 v[156:159], v71
	v_add_u32_e32 v160, v90, v197
	v_add_u32_e32 v161, s8, v89
	v_subrev_co_u32_e32 v88, vcc, 1, v88
	s_waitcnt vmcnt(3) lgkmcnt(2)
	v_mfma_f32_32x32x16_bf16 v[34:49], v[34:37], v[50:53], 0
	v_cmp_gt_i32_e64 s[0:1], v161, v78
	v_cmp_ge_i32_e64 s[10:11], v161, v78
	v_add_u32_e32 v71, 2, v161
	s_and_b64 s[0:1], vcc, s[0:1]
	v_cmp_gt_i32_e64 s[12:13], v71, v78
	v_add_u32_e32 v163, 8, v161
	v_add_u32_e32 v164, 9, v161
	s_waitcnt vmcnt(2) lgkmcnt(1)
	v_mfma_f32_32x32x16_bf16 v[34:49], v[152:155], v[54:57], v[34:49]
	ds_read_b128 v[152:155], v160
	v_add_u32_e32 v210, v149, v197
	v_add_u32_e32 v211, v150, v197
	ds_read2_b64 v[216:219], v210 offset1:2
	ds_read2_b64 v[220:223], v211 offset1:2
	ds_read2_b64 v[224:227], v210 offset0:4 offset1:6
	ds_read2_b64 v[228:231], v211 offset0:4 offset1:6
	v_add_u32_e32 v160, 3, v161
	v_cmp_gt_i32_e64 s[14:15], v160, v78
	v_cmp_gt_i32_e64 s[16:17], v163, v78
	v_cmp_gt_i32_e64 s[18:19], v164, v78
	s_waitcnt vmcnt(1) lgkmcnt(5)
	v_mfma_f32_32x32x16_bf16 v[34:49], v[156:159], v[58:61], v[34:49]
	v_add_u32_e32 v156, 10, v161
	v_cmp_gt_i32_e64 s[20:21], v156, v78
	v_add_u32_e32 v157, 11, v161
	s_waitcnt vmcnt(0) lgkmcnt(4)
	v_mfma_f32_32x32x16_bf16 v[34:49], v[152:155], v[62:65], v[34:49]
	s_nop 11
	v_cndmask_b32_e64 v34, v34, v143, s[0:1]
	s_and_b64 s[0:1], vcc, s[10:11]
	v_cndmask_b32_e64 v152, v35, v143, s[0:1]
	s_and_b64 s[0:1], vcc, s[12:13]
	v_cndmask_b32_e64 v153, v36, v143, s[0:1]
	s_and_b64 s[0:1], vcc, s[14:15]
	v_cndmask_b32_e64 v37, v37, v143, s[0:1]
	s_and_b64 s[0:1], vcc, s[16:17]
	v_cndmask_b32_e64 v38, v38, v143, s[0:1]
	s_and_b64 s[0:1], vcc, s[18:19]
	v_cndmask_b32_e64 v154, v39, v143, s[0:1]
	s_and_b64 s[0:1], vcc, s[20:21]
	v_cndmask_b32_e64 v40, v40, v143, s[0:1]
	v_cmp_gt_i32_e64 s[0:1], v157, v78
	s_and_b64 s[0:1], vcc, s[0:1]
	v_add_u32_e32 v36, 16, v161
	v_cndmask_b32_e64 v155, v41, v143, s[0:1]
	v_cmp_gt_i32_e64 s[0:1], v36, v78
	s_and_b64 s[0:1], vcc, s[0:1]
	v_add_u32_e32 v36, 17, v161
	v_cndmask_b32_e64 v42, v42, v143, s[0:1]
	v_cmp_gt_i32_e64 s[0:1], v36, v78
	s_and_b64 s[0:1], vcc, s[0:1]
	v_add_u32_e32 v36, 18, v161
	v_cndmask_b32_e64 v156, v43, v143, s[0:1]
	v_cmp_gt_i32_e64 s[0:1], v36, v78
	s_and_b64 s[0:1], vcc, s[0:1]
	v_add_u32_e32 v36, 19, v161
	v_cndmask_b32_e64 v44, v44, v143, s[0:1]
	v_cmp_gt_i32_e64 s[0:1], v36, v78
	s_and_b64 s[0:1], vcc, s[0:1]
	v_add_u32_e32 v36, 24, v161
	v_cndmask_b32_e64 v157, v45, v143, s[0:1]
	v_cmp_gt_i32_e64 s[0:1], v36, v78
	s_and_b64 s[0:1], vcc, s[0:1]
	v_add_u32_e32 v36, 25, v161
	v_max3_f32 v35, v34, s22, v152
	v_cndmask_b32_e64 v46, v46, v143, s[0:1]
	v_cmp_gt_i32_e64 s[0:1], v36, v78
	v_max3_f32 v35, v35, v153, v37
	s_and_b64 s[0:1], vcc, s[0:1]
	v_add_u32_e32 v36, 26, v161
	v_max3_f32 v35, v35, v38, v154
	v_cndmask_b32_e64 v158, v47, v143, s[0:1]
	v_cmp_gt_i32_e64 s[0:1], v36, v78
	v_max3_f32 v35, v35, v40, v155
	s_and_b64 s[0:1], vcc, s[0:1]
	v_add_u32_e32 v36, 27, v161
	v_max3_f32 v35, v35, v42, v156
	v_cndmask_b32_e64 v48, v48, v143, s[0:1]
	v_cmp_gt_i32_e64 s[0:1], v36, v78
	v_max3_f32 v35, v35, v44, v157
	s_and_b64 vcc, vcc, s[0:1]
	v_max3_f32 v35, v35, v46, v158
	v_cndmask_b32_e32 v159, v49, v143, vcc
	v_max3_f32 v35, v35, v48, v159
	v_mov_b32_e32 v36, v35
	s_nop 1
	v_permlane32_swap_b32_e32 v35, v36
	v_max_f32_e32 v36, v36, v36
	v_max_f32_e32 v35, v35, v35
	v_max_f32_e32 v35, v35, v36
	v_mul_f32_e32 v35, 0x3e38aa3b, v35
	v_max_f32_e32 v36, v0, v0
	v_max_f32_e32 v71, v36, v35
	v_fma_f32 v34, v34, s23, -v71
	v_exp_f32_e32 v35, v34
	v_fma_f32 v34, v152, s23, -v71
	v_exp_f32_e32 v36, v34
	v_fma_f32 v34, v153, s23, -v71
	v_exp_f32_e32 v39, v34
	v_fma_f32 v34, v37, s23, -v71
	v_exp_f32_e32 v41, v34
	v_fma_f32 v37, v38, s23, -v71
	v_add_f32_e32 v34, 0, v35
	v_exp_f32_e32 v43, v37
	v_fma_f32 v37, v154, s23, -v71
	v_add_f32_e32 v34, v36, v34
	v_exp_f32_e32 v45, v37
	v_fma_f32 v37, v40, s23, -v71
	v_add_f32_e32 v34, v39, v34
	v_exp_f32_e32 v47, v37
	v_fma_f32 v37, v155, s23, -v71
	v_add_f32_e32 v34, v41, v34
	v_exp_f32_e32 v49, v37
	v_add_f32_e32 v34, v43, v34
	v_add_f32_e32 v34, v45, v34
	v_add_f32_e32 v34, v47, v34
	v_add_f32_e32 v152, v49, v34
	v_fma_f32 v34, v42, s23, -v71
	v_exp_f32_e32 v34, v34
	v_fma_f32 v37, v156, s23, -v71
	v_exp_f32_e32 v37, v37
	v_fma_f32 v38, v44, s23, -v71
	v_exp_f32_e32 v38, v38
	v_fma_f32 v40, v157, s23, -v71
	v_exp_f32_e32 v40, v40
	v_add_f32_e32 v42, v34, v152
	v_add_f32_e32 v42, v37, v42
	v_add_f32_e32 v42, v38, v42
	v_add_f32_e32 v152, v40, v42
	v_fma_f32 v42, v46, s23, -v71
	v_exp_f32_e32 v42, v42
	v_fma_f32 v44, v158, s23, -v71
	v_exp_f32_e32 v44, v44
	v_fma_f32 v46, v48, s23, -v71
	v_exp_f32_e32 v46, v46
	v_fma_f32 v48, v159, s23, -v71
	v_exp_f32_e32 v48, v48
	v_sub_f32_e32 v0, v0, v71
	v_add_f32_e32 v152, v42, v152
	v_add_f32_e32 v152, v44, v152
	v_exp_f32_e32 v0, v0
	v_add_f32_e32 v152, v46, v152
	v_add_f32_e32 v152, v48, v152
	v_mov_b32_e32 v153, v152
	s_nop 1
	v_permlane32_swap_b32_e32 v152, v153
	v_cmp_neq_f32_e32 vcc, 1.0, v0
	s_cbranch_vccz .LBB0_792
	v_pk_mul_f32 v[32:33], v[32:33], v[0:1] op_sel_hi:[1,0]
	v_pk_mul_f32 v[30:31], v[30:31], v[0:1] op_sel_hi:[1,0]
	v_pk_mul_f32 v[28:29], v[28:29], v[0:1] op_sel_hi:[1,0]
	v_pk_mul_f32 v[26:27], v[26:27], v[0:1] op_sel_hi:[1,0]
	v_pk_mul_f32 v[24:25], v[24:25], v[0:1] op_sel_hi:[1,0]
	v_pk_mul_f32 v[22:23], v[22:23], v[0:1] op_sel_hi:[1,0]
	v_pk_mul_f32 v[20:21], v[20:21], v[0:1] op_sel_hi:[1,0]
	v_pk_mul_f32 v[18:19], v[18:19], v[0:1] op_sel_hi:[1,0]
	v_pk_mul_f32 v[16:17], v[16:17], v[0:1] op_sel_hi:[1,0]
	v_pk_mul_f32 v[14:15], v[14:15], v[0:1] op_sel_hi:[1,0]
	v_pk_mul_f32 v[12:13], v[12:13], v[0:1] op_sel_hi:[1,0]
	v_pk_mul_f32 v[10:11], v[10:11], v[0:1] op_sel_hi:[1,0]
	v_pk_mul_f32 v[8:9], v[8:9], v[0:1] op_sel_hi:[1,0]
	v_pk_mul_f32 v[6:7], v[6:7], v[0:1] op_sel_hi:[1,0]
	v_pk_mul_f32 v[4:5], v[4:5], v[0:1] op_sel_hi:[1,0]
	v_pk_mul_f32 v[2:3], v[2:3], v[0:1] op_sel_hi:[1,0]
.LBB0_792:
	v_cvt_pk_bf16_f32 v158, v35, v36
	v_cvt_pk_bf16_f32 v159, v39, v41
	v_cvt_pk_bf16_f32 v160, v43, v45
	v_cvt_pk_bf16_f32 v161, v47, v49
	v_add_f32_e32 v36, v152, v153
	v_cvt_pk_bf16_f32 v153, v38, v40
	v_cvt_pk_bf16_f32 v152, v34, v37
	s_waitcnt lgkmcnt(0)
	v_mfma_f32_32x32x16_bf16 v[18:33], v[216:219], v[158:161], v[18:33]
	s_add_i32 s8, s8, 32
	v_fmac_f32_e32 v36, v151, v0
	v_add_u32_e32 v150, 64, v150
	v_add_u32_e32 v149, 64, v149
	v_add_u32_e32 v148, 0x1000, v148
	v_mfma_f32_32x32x16_bf16 v[2:17], v[220:223], v[158:161], v[2:17]
	v_cvt_pk_bf16_f32 v154, v42, v44
	v_cvt_pk_bf16_f32 v155, v46, v48
	v_add_u32_e32 v147, 0x1000, v147
	v_add_u32_e32 v91, 0x1000, v91
	v_add_u32_e32 v90, 0x1000, v90
	s_cmpk_eq_i32 s8, 0x100
	v_mfma_f32_32x32x16_bf16 v[18:33], v[224:227], v[152:155], v[18:33]
	v_mfma_f32_32x32x16_bf16 v[2:17], v[228:231], v[152:155], v[2:17]
	s_cbranch_scc1 .LBB0_798
	v_mov_b32_e32 v151, v36
	s_branch .LBB0_790

; DI unsigned pack2bf(float a, float b) { const f2_t v = {a, b}; return __builtin_bit_cast(unsigned, __builtin_convertvector(v, bf2_t)); }
; DI void attn_task(const Params& P, int bh, int n, int t, int lane, const char* Ks, const char* Vs) {
;     ...
; #pragma unroll
;     for (int s = 0; s < 2; ++s) {
;       const uint4 ppk = make_uint4(pack2bf(S[8 * s], S[8 * s + 1]), pack2bf(S[8 * s + 2], S[8 * s + 3]), pack2bf(S[8 * s + 4], S[8 * s + 5]), pack2bf(S[8 * s + 6], S[8 * s + 7]));
;       const bf16x8 pf = __builtin_bit_cast(bf16x8, ppk);
; #pragma unroll
;       for (int dt = 0; dt < 2; ++dt) {
;         const char* vp = Vs + (dt * 32 + r) * 528 + (kt * 32 + 16 * s + 4 * hh) * 2;
;         const uint2 lo = *reinterpret_cast<const uint2*>(vp), hi = *reinterpret_cast<const uint2*>(vp + 16);
;         const uint4 vv = make_uint4(lo.x, lo.y, hi.x, hi.y);
;         if (dt == 0) O0 = __builtin_amdgcn_mfma_f32_32x32x16_bf16(__builtin_bit_cast(bf16x8, vv), pf, O0, 0, 0, 0);
;         else O1 = __builtin_amdgcn_mfma_f32_32x32x16_bf16(__builtin_bit_cast(bf16x8, vv), pf, O1, 0, 0, 0);
;       }
;     }
.LBB0_803:
	v_cvt_pk_bf16_f32 v164, v36, v39
	v_cvt_pk_bf16_f32 v165, v40, v42
	v_cvt_pk_bf16_f32 v166, v44, v47
	v_cvt_pk_bf16_f32 v167, v48, v152
	v_add_f32_e32 v36, v153, v154
	v_cvt_pk_bf16_f32 v40, v35, v37
	v_cvt_pk_bf16_f32 v41, v38, v41
	s_waitcnt lgkmcnt(0)
	v_mfma_f32_32x32x16_bf16 v[2:17], v[216:219], v[164:167], v[2:17]
	v_cvt_pk_bf16_f32 v42, v43, v45
	v_cvt_pk_bf16_f32 v43, v46, v49
	v_add_u32_e32 v88, -1, v88
	v_fmac_f32_e32 v36, v151, v34
	v_cmp_eq_u32_e32 vcc, 0, v88
	v_mfma_f32_32x32x16_bf16 v[2:17], v[224:227], v[40:43], v[2:17]
	v_add_u32_e32 v150, 64, v150
	v_add_u32_e32 v149, 64, v149
	v_add_u32_e32 v148, 0x1000, v148
	v_add_u32_e32 v147, 0x1000, v147
	v_add_u32_e32 v91, 0x1000, v91
	v_add_u32_e32 v90, 0x1000, v90
	v_add_u32_e32 v89, 32, v89
	v_mfma_f32_32x32x16_bf16 v[18:33], v[220:223], v[164:167], v[18:33]
	s_or_b64 s[60:61], vcc, s[60:61]
	v_mov_b32_e32 v151, v36
	v_mfma_f32_32x32x16_bf16 v[18:33], v[228:231], v[40:43], v[18:33]
	s_andn2_b64 exec, exec, s[60:61]
	s_cbranch_execz .LBB0_806
; DI float xor32_max(float v) { const auto r = __builtin_amdgcn_permlane32_swap(__float_as_uint(v), __float_as_uint(v), false, false); return fmaxf(__uint_as_float(r[0]), __uint_as_float(r[1])); }
; DI float xor32_sum(float v) { const auto r = __builtin_amdgcn_permlane32_swap(__float_as_uint(v), __float_as_uint(v), false, false); return __uint_as_float(r[0]) + __uint_as_float(r[1]); }
; DI int crow(int i, int hh) { return (i & 3) + 8 * (i >> 2) + 4 * hh; }
; DI void attn_task(const Params& P, int bh, int n, int t, int lane, const char* Ks, const char* Vs) {
;     ...
;   for (int kt = 0; kt < nkt; ++kt) {
;     const int kbase = n * 256 + kt * 32;
;     const int krow = kt * 32 + r;
;     f32x16 S;
; #pragma unroll
;     for (int i = 0; i < 16; ++i) S[i] = 0.f;
; #pragma unroll
;     for (int s = 0; s < 4; ++s) {
;       const bf16x8 kf = *reinterpret_cast<const bf16x8*>(Ks + krow * 128 + (((2 * s + hh) ^ ((krow >> 1) & 7)) * 16));
;       S = __builtin_amdgcn_mfma_f32_32x32x16_bf16(kf, qf[s], S, 0, 0, 0);
;     }
;     const bool diag = own && (kt == t);
;     constexpr float SC2 = 0.125f * 1.4426950408889634f;
;     float mx = -1e30f;
; #pragma unroll
;     for (int i = 0; i < 16; ++i) {
;       if (diag && (kbase + crow(i, hh) > lq)) S[i] = -1e30f;
;       mx = fmaxf(mx, S[i]);
;     }
;     mx = xor32_max(mx);
;     const float m_new = fmaxf(m_run, mx * SC2);
;     const float alpha = __builtin_amdgcn_exp2f(m_run - m_new);
;     float rs = 0.f;
; #pragma unroll
;     for (int i = 0; i < 16; ++i) { float pv = __builtin_amdgcn_exp2f(fmaf(S[i], SC2, -m_new)); S[i] = pv; rs += pv; }
;     rs = xor32_sum(rs);
;     l_run = l_run * alpha + rs; m_run = m_new;
;     if (__ballot(alpha != 1.f)) {
; #pragma unroll
;       for (int i = 0; i < 16; ++i) { O0[i] *= alpha; O1[i] *= alpha; }
.LBB0_804:
	v_add_u32_e32 v34, v148, v197
	ds_read_b128 v[34:37], v34
	v_add_u32_e32 v38, v147, v197
	ds_read_b128 v[152:155], v38
	v_mov_b32_e32 v160, v79
	v_add_u32_e32 v79, v91, v197
	ds_read_b128 v[156:159], v79
	v_add_u32_e32 v161, v90, v197
	v_subrev_u32_e32 v163, 27, v89
	v_cmp_eq_u32_e32 vcc, 1, v88
	s_waitcnt vmcnt(3) lgkmcnt(2)
	v_mfma_f32_32x32x16_bf16 v[34:49], v[34:37], v[50:53], 0
	v_cmp_gt_i32_e64 s[0:1], v163, v78
	v_subrev_u32_e32 v164, 25, v89
	v_cmp_ge_i32_e64 s[10:11], v163, v78
	s_and_b64 s[0:1], vcc, s[0:1]
	v_subrev_u32_e32 v79, 24, v89
	v_cmp_gt_i32_e64 s[12:13], v164, v78
	v_subrev_u32_e32 v165, 19, v89
	s_waitcnt vmcnt(2) lgkmcnt(1)
	v_mfma_f32_32x32x16_bf16 v[34:49], v[152:155], v[54:57], v[34:49]
	ds_read_b128 v[152:155], v161
	v_add_u32_e32 v210, v149, v197
	v_add_u32_e32 v211, v150, v197
	ds_read2_b64 v[216:219], v210 offset1:2
	ds_read2_b64 v[220:223], v211 offset1:2
	ds_read2_b64 v[224:227], v210 offset0:4 offset1:6
	ds_read2_b64 v[228:231], v211 offset0:4 offset1:6
	v_cmp_gt_i32_e64 s[14:15], v79, v78
	v_subrev_u32_e32 v166, 18, v89
	v_cmp_gt_i32_e64 s[16:17], v165, v78
	v_subrev_u32_e32 v167, 17, v89
	v_cmp_gt_i32_e64 s[18:19], v166, v78
	v_add_u32_e32 v172, -16, v89
	s_waitcnt vmcnt(1) lgkmcnt(5)
	v_mfma_f32_32x32x16_bf16 v[34:49], v[156:159], v[58:61], v[34:49]
	v_cmp_gt_i32_e64 s[20:21], v167, v78
	v_cmp_gt_i32_e64 s[24:25], v172, v78
	s_waitcnt vmcnt(0) lgkmcnt(4)
	v_mfma_f32_32x32x16_bf16 v[34:49], v[152:155], v[62:65], v[34:49]
	s_nop 11
	v_cndmask_b32_e64 v34, v34, v143, s[0:1]
	s_and_b64 s[0:1], vcc, s[10:11]
	v_cndmask_b32_e64 v35, v35, v143, s[0:1]
	s_and_b64 s[0:1], vcc, s[12:13]
	v_cndmask_b32_e64 v152, v36, v143, s[0:1]
	s_and_b64 s[0:1], vcc, s[14:15]
	v_cndmask_b32_e64 v37, v37, v143, s[0:1]
	s_and_b64 s[0:1], vcc, s[16:17]
	v_cndmask_b32_e64 v38, v38, v143, s[0:1]
	s_and_b64 s[0:1], vcc, s[18:19]
	v_cndmask_b32_e64 v153, v39, v143, s[0:1]
	s_and_b64 s[0:1], vcc, s[20:21]
	v_cndmask_b32_e64 v154, v40, v143, s[0:1]
	s_and_b64 s[0:1], vcc, s[24:25]
	v_add_u32_e32 v39, -11, v89
	v_cndmask_b32_e64 v41, v41, v143, s[0:1]
	v_cmp_gt_i32_e64 s[0:1], v39, v78
	s_and_b64 s[0:1], vcc, s[0:1]
	v_add_u32_e32 v39, -10, v89
	v_cndmask_b32_e64 v155, v42, v143, s[0:1]
	v_cmp_gt_i32_e64 s[0:1], v39, v78
	s_and_b64 s[0:1], vcc, s[0:1]
	v_add_u32_e32 v39, -9, v89
	v_cndmask_b32_e64 v43, v43, v143, s[0:1]
	v_cmp_gt_i32_e64 s[0:1], v39, v78
	s_and_b64 s[0:1], vcc, s[0:1]
	v_add_u32_e32 v39, -8, v89
	v_cndmask_b32_e64 v156, v44, v143, s[0:1]
	v_cmp_gt_i32_e64 s[0:1], v39, v78
	s_and_b64 s[0:1], vcc, s[0:1]
	v_add_u32_e32 v39, -3, v89
	v_cndmask_b32_e64 v45, v45, v143, s[0:1]
	v_cmp_gt_i32_e64 s[0:1], v39, v78
	s_and_b64 s[0:1], vcc, s[0:1]
	v_add_u32_e32 v39, -2, v89
	v_max3_f32 v36, v34, s22, v35
	v_cndmask_b32_e64 v46, v46, v143, s[0:1]
	v_cmp_gt_i32_e64 s[0:1], v39, v78
	v_max3_f32 v36, v36, v152, v37
	s_and_b64 s[0:1], vcc, s[0:1]
	v_add_u32_e32 v39, -1, v89
	v_max3_f32 v36, v36, v38, v153
	v_cndmask_b32_e64 v157, v47, v143, s[0:1]
	v_cmp_gt_i32_e64 s[0:1], v39, v78
	v_max3_f32 v36, v36, v154, v41
	s_and_b64 s[0:1], vcc, s[0:1]
	v_max3_f32 v36, v36, v155, v43
	v_cndmask_b32_e64 v158, v48, v143, s[0:1]
	v_cmp_gt_i32_e64 s[0:1], v89, v78
	v_max3_f32 v36, v36, v156, v45
	s_and_b64 vcc, vcc, s[0:1]
	v_max3_f32 v36, v36, v46, v157
	v_cndmask_b32_e32 v49, v49, v143, vcc
	v_max3_f32 v36, v36, v158, v49
	v_mov_b32_e32 v39, v36
	s_nop 1
	v_permlane32_swap_b32_e32 v36, v39
	v_max_f32_e32 v39, v39, v39
	v_max_f32_e32 v36, v36, v36
	v_max_f32_e32 v36, v36, v39
	v_mul_f32_e32 v36, 0x3e38aa3b, v36
	v_max_f32_e32 v39, v160, v160
	v_max_f32_e32 v79, v39, v36
	v_fma_f32 v34, v34, s23, -v79
	v_exp_f32_e32 v36, v34
	v_fma_f32 v34, v35, s23, -v79
	v_exp_f32_e32 v39, v34
	v_fma_f32 v34, v152, s23, -v79
	v_exp_f32_e32 v40, v34
	v_fma_f32 v34, v37, s23, -v79
	v_exp_f32_e32 v42, v34
	v_fma_f32 v35, v38, s23, -v79
	v_add_f32_e32 v34, 0, v36
	v_exp_f32_e32 v44, v35
	v_fma_f32 v35, v153, s23, -v79
	v_add_f32_e32 v34, v39, v34
	v_exp_f32_e32 v47, v35
	v_fma_f32 v35, v154, s23, -v79
	v_add_f32_e32 v34, v40, v34
	v_exp_f32_e32 v48, v35
	v_fma_f32 v35, v41, s23, -v79
	v_add_f32_e32 v34, v42, v34
	v_exp_f32_e32 v152, v35
	v_fma_f32 v35, v155, s23, -v79
	v_add_f32_e32 v34, v44, v34
	v_exp_f32_e32 v35, v35
	v_fma_f32 v37, v43, s23, -v79
	v_add_f32_e32 v34, v47, v34
	v_exp_f32_e32 v37, v37
	v_fma_f32 v38, v156, s23, -v79
	v_add_f32_e32 v34, v48, v34
	v_exp_f32_e32 v38, v38
	v_fma_f32 v41, v45, s23, -v79
	v_add_f32_e32 v34, v152, v34
	v_exp_f32_e32 v41, v41
	v_fma_f32 v43, v46, s23, -v79
	v_add_f32_e32 v34, v35, v34
	v_exp_f32_e32 v43, v43
	v_fma_f32 v45, v157, s23, -v79
	v_add_f32_e32 v34, v37, v34
	v_exp_f32_e32 v45, v45
	v_fma_f32 v46, v158, s23, -v79
	v_add_f32_e32 v34, v38, v34
	v_exp_f32_e32 v46, v46
	v_fma_f32 v49, v49, s23, -v79
	v_add_f32_e32 v34, v41, v34
	v_exp_f32_e32 v49, v49
	v_add_f32_e32 v34, v43, v34
	v_add_f32_e32 v34, v45, v34
	v_sub_f32_e32 v159, v160, v79
	v_add_f32_e32 v34, v46, v34
	v_add_f32_e32 v153, v49, v34
	v_exp_f32_e32 v34, v159
	v_mov_b32_e32 v154, v153
	s_nop 1
	v_permlane32_swap_b32_e32 v153, v154
	v_cmp_neq_f32_e32 vcc, 1.0, v34
	s_cbranch_vccz .LBB0_803
	v_pk_mul_f32 v[16:17], v[16:17], v[34:35] op_sel_hi:[1,0]
	v_pk_mul_f32 v[14:15], v[14:15], v[34:35] op_sel_hi:[1,0]
	v_pk_mul_f32 v[12:13], v[12:13], v[34:35] op_sel_hi:[1,0]
	v_pk_mul_f32 v[10:11], v[10:11], v[34:35] op_sel_hi:[1,0]
	v_pk_mul_f32 v[8:9], v[8:9], v[34:35] op_sel_hi:[1,0]
	v_pk_mul_f32 v[6:7], v[6:7], v[34:35] op_sel_hi:[1,0]
	v_pk_mul_f32 v[4:5], v[4:5], v[34:35] op_sel_hi:[1,0]
	v_pk_mul_f32 v[2:3], v[2:3], v[34:35] op_sel_hi:[1,0]
	v_pk_mul_f32 v[32:33], v[32:33], v[34:35] op_sel_hi:[1,0]
	v_pk_mul_f32 v[30:31], v[30:31], v[34:35] op_sel_hi:[1,0]
	v_pk_mul_f32 v[28:29], v[28:29], v[34:35] op_sel_hi:[1,0]
	v_pk_mul_f32 v[26:27], v[26:27], v[34:35] op_sel_hi:[1,0]
	v_pk_mul_f32 v[24:25], v[24:25], v[34:35] op_sel_hi:[1,0]
	v_pk_mul_f32 v[22:23], v[22:23], v[34:35] op_sel_hi:[1,0]
	v_pk_mul_f32 v[20:21], v[20:21], v[34:35] op_sel_hi:[1,0]
	v_pk_mul_f32 v[18:19], v[18:19], v[34:35] op_sel_hi:[1,0]
	s_branch .LBB0_803

; DI unsigned pack2bf(float a, float b) { const f2_t v = {a, b}; return __builtin_bit_cast(unsigned, __builtin_convertvector(v, bf2_t)); }
; DI void attn_task(const Params& P, int bh, int n, int t, int lane, const char* Ks, const char* Vs) {
;     ...
; #pragma unroll
;     for (int s = 0; s < 2; ++s) {
;       const uint4 ppk = make_uint4(pack2bf(S[8 * s], S[8 * s + 1]), pack2bf(S[8 * s + 2], S[8 * s + 3]), pack2bf(S[8 * s + 4], S[8 * s + 5]), pack2bf(S[8 * s + 6], S[8 * s + 7]));
;       const bf16x8 pf = __builtin_bit_cast(bf16x8, ppk);
; #pragma unroll
;       for (int dt = 0; dt < 2; ++dt) {
;         const char* vp = Vs + (dt * 32 + r) * 528 + (kt * 32 + 16 * s + 4 * hh) * 2;
;         const uint2 lo = *reinterpret_cast<const uint2*>(vp), hi = *reinterpret_cast<const uint2*>(vp + 16);
;         const uint4 vv = make_uint4(lo.x, lo.y, hi.x, hi.y);
;         if (dt == 0) O0 = __builtin_amdgcn_mfma_f32_32x32x16_bf16(__builtin_bit_cast(bf16x8, vv), pf, O0, 0, 0, 0);
;         else O1 = __builtin_amdgcn_mfma_f32_32x32x16_bf16(__builtin_bit_cast(bf16x8, vv), pf, O1, 0, 0, 0);
;       }
;     }
.LBB0_814:
	v_cvt_pk_bf16_f32 v164, v36, v38
	v_cvt_pk_bf16_f32 v165, v40, v41
	v_cvt_pk_bf16_f32 v166, v44, v46
	v_cvt_pk_bf16_f32 v167, v48, v49
	v_add_f32_e32 v36, v153, v154
	v_fmac_f32_e32 v36, v152, v0
	s_waitcnt lgkmcnt(0)
	v_mfma_f32_32x32x16_bf16 v[18:33], v[216:219], v[164:167], v[18:33]
	v_cvt_pk_bf16_f32 v39, v37, v39
	v_cvt_pk_bf16_f32 v40, v42, v43
	v_cvt_pk_bf16_f32 v41, v45, v47
	s_add_i32 s8, s8, 32
	v_cmp_eq_u32_e32 vcc, s8, v89
	v_add_u32_e32 v151, 64, v151
	v_add_u32_e32 v150, 64, v150
	v_mfma_f32_32x32x16_bf16 v[2:17], v[220:223], v[164:167], v[2:17]
	v_cvt_pk_bf16_f32 v38, v34, v35
	v_add_u32_e32 v149, 0x1000, v149
	v_add_u32_e32 v148, 0x1000, v148
	v_add_u32_e32 v147, 0x1000, v147
	v_add_u32_e32 v91, 0x1000, v91
	s_or_b64 s[58:59], vcc, s[58:59]
	v_mfma_f32_32x32x16_bf16 v[18:33], v[224:227], v[38:41], v[18:33]
	v_mov_b32_e32 v152, v36
	v_mfma_f32_32x32x16_bf16 v[2:17], v[228:231], v[38:41], v[2:17]
	s_andn2_b64 exec, exec, s[58:59]
	s_cbranch_execz .LBB0_817
; DI float xor32_max(float v) { const auto r = __builtin_amdgcn_permlane32_swap(__float_as_uint(v), __float_as_uint(v), false, false); return fmaxf(__uint_as_float(r[0]), __uint_as_float(r[1])); }
; DI float xor32_sum(float v) { const auto r = __builtin_amdgcn_permlane32_swap(__float_as_uint(v), __float_as_uint(v), false, false); return __uint_as_float(r[0]) + __uint_as_float(r[1]); }
; DI int crow(int i, int hh) { return (i & 3) + 8 * (i >> 2) + 4 * hh; }
; DI void attn_task(const Params& P, int bh, int n, int t, int lane, const char* Ks, const char* Vs) {
;     ...
;   for (int kt = 0; kt < nkt; ++kt) {
;     const int kbase = n * 256 + kt * 32;
;     const int krow = kt * 32 + r;
;     f32x16 S;
; #pragma unroll
;     for (int i = 0; i < 16; ++i) S[i] = 0.f;
; #pragma unroll
;     for (int s = 0; s < 4; ++s) {
;       const bf16x8 kf = *reinterpret_cast<const bf16x8*>(Ks + krow * 128 + (((2 * s + hh) ^ ((krow >> 1) & 7)) * 16));
;       S = __builtin_amdgcn_mfma_f32_32x32x16_bf16(kf, qf[s], S, 0, 0, 0);
;     }
;     const bool diag = own && (kt == t);
;     constexpr float SC2 = 0.125f * 1.4426950408889634f;
;     float mx = -1e30f;
; #pragma unroll
;     for (int i = 0; i < 16; ++i) {
;       if (diag && (kbase + crow(i, hh) > lq)) S[i] = -1e30f;
;       mx = fmaxf(mx, S[i]);
;     }
;     mx = xor32_max(mx);
;     const float m_new = fmaxf(m_run, mx * SC2);
;     const float alpha = __builtin_amdgcn_exp2f(m_run - m_new);
;     float rs = 0.f;
; #pragma unroll
;     for (int i = 0; i < 16; ++i) { float pv = __builtin_amdgcn_exp2f(fmaf(S[i], SC2, -m_new)); S[i] = pv; rs += pv; }
;     rs = xor32_sum(rs);
;     l_run = l_run * alpha + rs; m_run = m_new;
;     if (__ballot(alpha != 1.f)) {
; #pragma unroll
;       for (int i = 0; i < 16; ++i) { O0[i] *= alpha; O1[i] *= alpha; }
.LBB0_815:
	v_add_u32_e32 v0, v149, v197
	ds_read_b128 v[34:37], v0
	v_add_u32_e32 v0, v148, v197
	ds_read_b128 v[154:157], v0
	v_mov_b32_e32 v0, v71
	v_add_u32_e32 v71, v147, v197
	ds_read_b128 v[158:161], v71
	v_add_u32_e32 v153, v91, v197
	v_add_u32_e32 v163, s8, v90
	v_subrev_co_u32_e32 v88, vcc, 1, v88
	s_waitcnt vmcnt(3) lgkmcnt(2)
	v_mfma_f32_32x32x16_bf16 v[34:49], v[34:37], v[50:53], 0
	v_cmp_gt_i32_e64 s[0:1], v163, v79
	v_cmp_ge_i32_e64 s[10:11], v163, v79
	v_add_u32_e32 v71, 2, v163
	s_and_b64 s[0:1], vcc, s[0:1]
	v_cmp_gt_i32_e64 s[12:13], v71, v79
	v_add_u32_e32 v164, 8, v163
	v_add_u32_e32 v165, 9, v163
	s_waitcnt vmcnt(2) lgkmcnt(1)
	v_mfma_f32_32x32x16_bf16 v[34:49], v[154:157], v[54:57], v[34:49]
	ds_read_b128 v[154:157], v153
	v_add_u32_e32 v210, v150, v197
	v_add_u32_e32 v211, v151, v197
	ds_read2_b64 v[216:219], v210 offset1:2
	ds_read2_b64 v[220:223], v211 offset1:2
	ds_read2_b64 v[224:227], v210 offset0:4 offset1:6
	ds_read2_b64 v[228:231], v211 offset0:4 offset1:6
	v_add_u32_e32 v153, 3, v163
	v_cmp_gt_i32_e64 s[14:15], v153, v79
	v_cmp_gt_i32_e64 s[16:17], v164, v79
	v_cmp_gt_i32_e64 s[18:19], v165, v79
	s_waitcnt vmcnt(1) lgkmcnt(5)
	v_mfma_f32_32x32x16_bf16 v[34:49], v[158:161], v[58:61], v[34:49]
	v_add_u32_e32 v158, 10, v163
	v_cmp_gt_i32_e64 s[20:21], v158, v79
	v_add_u32_e32 v159, 11, v163
	s_waitcnt vmcnt(0) lgkmcnt(4)
	v_mfma_f32_32x32x16_bf16 v[34:49], v[154:157], v[62:65], v[34:49]
	s_nop 11
	v_cndmask_b32_e64 v34, v34, v143, s[0:1]
	s_and_b64 s[0:1], vcc, s[10:11]
	v_cndmask_b32_e64 v35, v35, v143, s[0:1]
	s_and_b64 s[0:1], vcc, s[12:13]
	v_cndmask_b32_e64 v153, v36, v143, s[0:1]
	s_and_b64 s[0:1], vcc, s[14:15]
	v_cndmask_b32_e64 v37, v37, v143, s[0:1]
	s_and_b64 s[0:1], vcc, s[16:17]
	v_cndmask_b32_e64 v154, v38, v143, s[0:1]
	s_and_b64 s[0:1], vcc, s[18:19]
	v_cndmask_b32_e64 v39, v39, v143, s[0:1]
	s_and_b64 s[0:1], vcc, s[20:21]
	v_cndmask_b32_e64 v155, v40, v143, s[0:1]
	v_cmp_gt_i32_e64 s[0:1], v159, v79
	s_and_b64 s[0:1], vcc, s[0:1]
	v_add_u32_e32 v38, 16, v163
	v_cndmask_b32_e64 v156, v41, v143, s[0:1]
	v_cmp_gt_i32_e64 s[0:1], v38, v79
	s_and_b64 s[0:1], vcc, s[0:1]
	v_add_u32_e32 v38, 17, v163
	v_cndmask_b32_e64 v42, v42, v143, s[0:1]
	v_cmp_gt_i32_e64 s[0:1], v38, v79
	s_and_b64 s[0:1], vcc, s[0:1]
	v_add_u32_e32 v38, 18, v163
	v_cndmask_b32_e64 v43, v43, v143, s[0:1]
	v_cmp_gt_i32_e64 s[0:1], v38, v79
	s_and_b64 s[0:1], vcc, s[0:1]
	v_add_u32_e32 v38, 19, v163
	v_cndmask_b32_e64 v157, v44, v143, s[0:1]
	v_cmp_gt_i32_e64 s[0:1], v38, v79
	s_and_b64 s[0:1], vcc, s[0:1]
	v_add_u32_e32 v38, 24, v163
	v_cndmask_b32_e64 v45, v45, v143, s[0:1]
	v_cmp_gt_i32_e64 s[0:1], v38, v79
	s_and_b64 s[0:1], vcc, s[0:1]
	v_add_u32_e32 v38, 25, v163
	v_max3_f32 v36, v34, s22, v35
	v_cndmask_b32_e64 v158, v46, v143, s[0:1]
	v_cmp_gt_i32_e64 s[0:1], v38, v79
	v_max3_f32 v36, v36, v153, v37
	s_and_b64 s[0:1], vcc, s[0:1]
	v_add_u32_e32 v38, 26, v163
	v_max3_f32 v36, v36, v154, v39
	v_cndmask_b32_e64 v47, v47, v143, s[0:1]
	v_cmp_gt_i32_e64 s[0:1], v38, v79
	v_max3_f32 v36, v36, v155, v156
	s_and_b64 s[0:1], vcc, s[0:1]
	v_add_u32_e32 v38, 27, v163
	v_max3_f32 v36, v36, v42, v43
	v_cndmask_b32_e64 v159, v48, v143, s[0:1]
	v_cmp_gt_i32_e64 s[0:1], v38, v79
	v_max3_f32 v36, v36, v157, v45
	s_and_b64 vcc, vcc, s[0:1]
	v_max3_f32 v36, v36, v158, v47
	v_cndmask_b32_e32 v160, v49, v143, vcc
	v_max3_f32 v36, v36, v159, v160
	v_mov_b32_e32 v38, v36
	s_nop 1
	v_permlane32_swap_b32_e32 v36, v38
	v_max_f32_e32 v38, v38, v38
	v_max_f32_e32 v36, v36, v36
	v_max_f32_e32 v36, v36, v38
	v_mul_f32_e32 v36, 0x3e38aa3b, v36
	v_max_f32_e32 v38, v0, v0
	v_max_f32_e32 v71, v38, v36
	v_fma_f32 v34, v34, s23, -v71
	v_exp_f32_e32 v36, v34
	v_fma_f32 v34, v35, s23, -v71
	v_exp_f32_e32 v38, v34
	v_fma_f32 v34, v153, s23, -v71
	v_exp_f32_e32 v40, v34
	v_fma_f32 v34, v37, s23, -v71
	v_exp_f32_e32 v41, v34
	v_fma_f32 v35, v154, s23, -v71
	v_add_f32_e32 v34, 0, v36
	v_exp_f32_e32 v44, v35
	v_fma_f32 v35, v39, s23, -v71
	v_add_f32_e32 v34, v38, v34
	v_exp_f32_e32 v46, v35
	v_fma_f32 v35, v155, s23, -v71
	v_add_f32_e32 v34, v40, v34
	v_exp_f32_e32 v48, v35
	v_fma_f32 v35, v156, s23, -v71
	v_add_f32_e32 v34, v41, v34
	v_exp_f32_e32 v49, v35
	v_add_f32_e32 v34, v44, v34
	v_add_f32_e32 v34, v46, v34
	v_add_f32_e32 v34, v48, v34
	v_add_f32_e32 v153, v49, v34
	v_fma_f32 v34, v42, s23, -v71
	v_exp_f32_e32 v34, v34
	v_fma_f32 v35, v43, s23, -v71
	v_exp_f32_e32 v35, v35
	v_fma_f32 v37, v157, s23, -v71
	v_exp_f32_e32 v37, v37
	v_fma_f32 v39, v45, s23, -v71
	v_exp_f32_e32 v39, v39
	v_add_f32_e32 v42, v34, v153
	v_add_f32_e32 v42, v35, v42
	v_add_f32_e32 v42, v37, v42
	v_add_f32_e32 v153, v39, v42
	v_fma_f32 v42, v158, s23, -v71
	v_exp_f32_e32 v42, v42
	v_fma_f32 v43, v47, s23, -v71
	v_exp_f32_e32 v43, v43
	v_fma_f32 v45, v159, s23, -v71
	v_exp_f32_e32 v45, v45
	v_fma_f32 v47, v160, s23, -v71
	v_exp_f32_e32 v47, v47
	v_sub_f32_e32 v0, v0, v71
	v_add_f32_e32 v153, v42, v153
	v_add_f32_e32 v153, v43, v153
	v_exp_f32_e32 v0, v0
	v_add_f32_e32 v153, v45, v153
	v_add_f32_e32 v153, v47, v153
	v_mov_b32_e32 v154, v153
	s_nop 1
	v_permlane32_swap_b32_e32 v153, v154
	v_cmp_neq_f32_e32 vcc, 1.0, v0
	s_cbranch_vccz .LBB0_814
	v_pk_mul_f32 v[32:33], v[32:33], v[0:1] op_sel_hi:[1,0]
	v_pk_mul_f32 v[30:31], v[30:31], v[0:1] op_sel_hi:[1,0]
	v_pk_mul_f32 v[28:29], v[28:29], v[0:1] op_sel_hi:[1,0]
	v_pk_mul_f32 v[26:27], v[26:27], v[0:1] op_sel_hi:[1,0]
	v_pk_mul_f32 v[24:25], v[24:25], v[0:1] op_sel_hi:[1,0]
	v_pk_mul_f32 v[22:23], v[22:23], v[0:1] op_sel_hi:[1,0]
	v_pk_mul_f32 v[20:21], v[20:21], v[0:1] op_sel_hi:[1,0]
	v_pk_mul_f32 v[18:19], v[18:19], v[0:1] op_sel_hi:[1,0]
	v_pk_mul_f32 v[16:17], v[16:17], v[0:1] op_sel_hi:[1,0]
	v_pk_mul_f32 v[14:15], v[14:15], v[0:1] op_sel_hi:[1,0]
	v_pk_mul_f32 v[12:13], v[12:13], v[0:1] op_sel_hi:[1,0]
	v_pk_mul_f32 v[10:11], v[10:11], v[0:1] op_sel_hi:[1,0]
	v_pk_mul_f32 v[8:9], v[8:9], v[0:1] op_sel_hi:[1,0]
	v_pk_mul_f32 v[6:7], v[6:7], v[0:1] op_sel_hi:[1,0]
	v_pk_mul_f32 v[4:5], v[4:5], v[0:1] op_sel_hi:[1,0]
	v_pk_mul_f32 v[2:3], v[2:3], v[0:1] op_sel_hi:[1,0]
	s_branch .LBB0_814
